# w_ff1 weight-conversion loops (GEMM idle tails and layer-0 phase C): 32 row loads back to back with one wait instead of a 2-11 deep sliding window
# baseline (speedup 1.0000x reference)
; __device__ __forceinline__ void transpose_item(const float* W, int K, int N, int NP, bf16* WT, LAS float* scr, int item, int lane, const LAS float* tab, long long* bias, int ldb, const float* kscale = nullptr) {
;     const int nblk = NP / 32, kb = item / nblk, nb = item - kb * nblk, k0 = 64 * kb, n0 = 32 * nb;
;     const int n = n0 + (lane & 31); const bool okn = n < N;
;     float wv_[32];
;     const float* wp = W + (size_t)(k0 + (lane >> 5)) * N + (okn ? n : 0);
; #pragma unroll
;     for (int i = 0; i < 32; ++i) wv_[i] = wp[(size_t)(2 * i) * N];
; #pragma unroll
;     for (int i = 0; i < 32; ++i) { if (!okn) wv_[i] = 0.f; if (kscale != nullptr) wv_[i] *= kscale[k0 + 2 * i + (lane >> 5)]; scr[(2 * i + (lane >> 5)) * 33 + (lane & 31)] = wv_[i]; }
.LBB0_102:
	s_ashr_i32 s4, s19, 31
	s_lshr_b32 s4, s4, 24
	s_add_i32 s22, s19, s4
	s_ashr_i32 s4, s22, 8
	s_lshl_b32 s17, s4, 13
	s_lshl_b32 s16, s4, 6
	s_sub_i32 s4, s18, s17
	v_add_u32_e32 v6, s4, v12
	v_or_b32_e32 v14, s16, v3
	v_ashrrev_i32_e32 v15, 31, v14
	v_cmp_gt_i32_e32 vcc, s93, v6
	v_lshlrev_b64 v[14:15], 15, v[14:15]
	v_lshl_add_u64 v[14:15], s[12:13], 0, v[14:15]
	v_cndmask_b32_e32 v16, 0, v6, vcc
	v_ashrrev_i32_e32 v17, 31, v16
	v_lshl_add_u64 v[14:15], v[16:17], 2, v[14:15]
	v_add_co_u32_e64 v16, s[4:5], s92, v14
	v_add_u32_e32 v77, 0x1c00, v13
	s_nop 0
	v_addc_co_u32_e64 v17, s[4:5], 0, v15, s[4:5]
	v_add_co_u32_e64 v18, s[4:5], s78, v14
	s_nop 1
	v_addc_co_u32_e64 v19, s[4:5], 0, v15, s[4:5]
	v_add_co_u32_e64 v20, s[4:5], s49, v14
	s_nop 1
	v_addc_co_u32_e64 v21, s[4:5], 0, v15, s[4:5]
	v_add_co_u32_e64 v22, s[4:5], s79, v14
	s_nop 1
	v_addc_co_u32_e64 v23, s[4:5], 0, v15, s[4:5]
	v_add_co_u32_e64 v24, s[4:5], s0, v14
	s_nop 1
	v_addc_co_u32_e64 v25, s[4:5], 0, v15, s[4:5]
	v_add_co_u32_e64 v26, s[4:5], s40, v14
	s_nop 1
	v_addc_co_u32_e64 v27, s[4:5], 0, v15, s[4:5]
	v_add_co_u32_e64 v28, s[4:5], s96, v14
	s_nop 1
	v_addc_co_u32_e64 v29, s[4:5], 0, v15, s[4:5]
	global_load_dword v7, v[14:15], off
	global_load_dword v45, v[16:17], off
	global_load_dword v44, v[18:19], off
	global_load_dword v43, v[20:21], off
	global_load_dword v42, v[22:23], off
	global_load_dword v41, v[24:25], off
	global_load_dword v40, v[26:27], off
	global_load_dword v39, v[28:29], off
	v_add_co_u32_e64 v16, s[4:5], s8, v14
	s_nop 1
	v_addc_co_u32_e64 v17, s[4:5], 0, v15, s[4:5]
	s_mov_b32 s4, 0x90000
	s_nop 0
	v_add_co_u32_e64 v18, s[4:5], s4, v14
	s_nop 1
	v_addc_co_u32_e64 v19, s[4:5], 0, v15, s[4:5]
	s_mov_b32 s4, 0xa0000
	s_nop 0
	v_add_co_u32_e64 v20, s[4:5], s4, v14
	s_nop 1
	v_addc_co_u32_e64 v21, s[4:5], 0, v15, s[4:5]
	s_mov_b32 s4, 0xb0000
	s_nop 0
	v_add_co_u32_e64 v22, s[4:5], s4, v14
	s_nop 1
	v_addc_co_u32_e64 v23, s[4:5], 0, v15, s[4:5]
	s_mov_b32 s4, 0xc0000
	s_nop 0
	v_add_co_u32_e64 v24, s[4:5], s4, v14
	s_nop 1
	v_addc_co_u32_e64 v25, s[4:5], 0, v15, s[4:5]
	s_mov_b32 s4, 0xd0000
	s_nop 0
	v_add_co_u32_e64 v26, s[4:5], s4, v14
	s_nop 0
	s_nop 0
	v_addc_co_u32_e64 v27, s[4:5], 0, v15, s[4:5]
	s_mov_b32 s4, 0xe0000
	s_nop 0
	v_add_co_u32_e64 v28, s[4:5], s4, v14
	s_nop 0
	s_nop 0
	v_addc_co_u32_e64 v29, s[4:5], 0, v15, s[4:5]
	s_mov_b32 s4, 0xf0000
	s_nop 0
	v_add_co_u32_e64 v30, s[4:5], s4, v14
	s_nop 0
	s_nop 0
	v_addc_co_u32_e64 v31, s[4:5], 0, v15, s[4:5]
	s_mov_b32 s4, 0x100000
	global_load_dword v38, v[16:17], off
	global_load_dword v37, v[18:19], off
	global_load_dword v36, v[20:21], off
	global_load_dword v35, v[22:23], off
	global_load_dword v34, v[24:25], off
	global_load_dword v32, v[26:27], off
	global_load_dword v46, v[28:29], off
	global_load_dword v47, v[30:31], off
	v_add_co_u32_e64 v16, s[4:5], s4, v14
	s_nop 0
	s_nop 0
	v_addc_co_u32_e64 v17, s[4:5], 0, v15, s[4:5]
	s_mov_b32 s4, 0x110000
	s_nop 0
	v_add_co_u32_e64 v18, s[4:5], s4, v14
	s_nop 0
	s_nop 0
	v_addc_co_u32_e64 v19, s[4:5], 0, v15, s[4:5]
	s_mov_b32 s4, 0x120000
	s_nop 0
	v_add_co_u32_e64 v20, s[4:5], s4, v14
	s_nop 0
	s_nop 0
	v_addc_co_u32_e64 v21, s[4:5], 0, v15, s[4:5]
	s_mov_b32 s4, 0x130000
	s_nop 0
	v_add_co_u32_e64 v22, s[4:5], s4, v14
	s_nop 0
	s_nop 0
	v_addc_co_u32_e64 v23, s[4:5], 0, v15, s[4:5]
	s_mov_b32 s4, 0x140000
	s_nop 0
	v_add_co_u32_e64 v24, s[4:5], s4, v14
	s_nop 0
	s_nop 0
	v_addc_co_u32_e64 v25, s[4:5], 0, v15, s[4:5]
	s_mov_b32 s4, 0x150000
	s_nop 0
	v_add_co_u32_e64 v26, s[4:5], s4, v14
	s_nop 0
	s_nop 0
	v_addc_co_u32_e64 v27, s[4:5], 0, v15, s[4:5]
	s_mov_b32 s4, 0x160000
	s_nop 0
	v_add_co_u32_e64 v28, s[4:5], s4, v14
	s_nop 0
	s_nop 0
	v_addc_co_u32_e64 v29, s[4:5], 0, v15, s[4:5]
	s_mov_b32 s4, 0x170000
	s_nop 0
	v_add_co_u32_e64 v30, s[4:5], s4, v14
	s_nop 1
	v_addc_co_u32_e64 v31, s[4:5], 0, v15, s[4:5]
	s_mov_b32 s4, 0x180000
	global_load_dword v48, v[16:17], off
	global_load_dword v49, v[18:19], off
	global_load_dword v50, v[20:21], off
	global_load_dword v51, v[22:23], off
	s_nop 0
	global_load_dword v25, v[24:25], off
	s_nop 0
	global_load_dword v24, v[26:27], off
	s_nop 0
	global_load_dword v26, v[28:29], off
	global_load_dword v27, v[30:31], off
	v_add_co_u32_e64 v16, s[4:5], s4, v14
	s_nop 1
	v_addc_co_u32_e64 v17, s[4:5], 0, v15, s[4:5]
	s_mov_b32 s4, 0x190000
	s_nop 0
	v_add_co_u32_e64 v18, s[4:5], s4, v14
	s_nop 1
	v_addc_co_u32_e64 v19, s[4:5], 0, v15, s[4:5]
	s_mov_b32 s4, 0x1a0000
	global_load_dword v28, v[16:17], off
	global_load_dword v29, v[18:19], off
	v_add_co_u32_e64 v16, s[4:5], s4, v14
	s_nop 1
	v_addc_co_u32_e64 v17, s[4:5], 0, v15, s[4:5]
	s_mov_b32 s4, 0x1b0000
	s_nop 0
	v_add_co_u32_e64 v18, s[4:5], s4, v14
	s_nop 1
	v_addc_co_u32_e64 v19, s[4:5], 0, v15, s[4:5]
	s_mov_b32 s4, 0x1c0000
	s_nop 0
	v_add_co_u32_e64 v20, s[4:5], s4, v14
	s_nop 1
	v_addc_co_u32_e64 v21, s[4:5], 0, v15, s[4:5]
	s_mov_b32 s4, 0x1d0000
	s_nop 0
	v_add_co_u32_e64 v22, s[4:5], s4, v14
	s_nop 1
	v_addc_co_u32_e64 v23, s[4:5], 0, v15, s[4:5]
	s_mov_b32 s4, 0x1e0000
	global_load_dword v30, v[16:17], off
	s_nop 0
	global_load_dword v18, v[18:19], off
	s_nop 0
	global_load_dword v19, v[20:21], off
	s_nop 0
	global_load_dword v20, v[22:23], off
	v_add_co_u32_e64 v16, s[4:5], s4, v14
	s_nop 1
	v_addc_co_u32_e64 v17, s[4:5], 0, v15, s[4:5]
	s_mov_b32 s4, 0x1f0000
	s_nop 0
	v_add_co_u32_e64 v14, s[4:5], s4, v14
	global_load_dword v16, v[16:17], off
	s_nop 0
	v_addc_co_u32_e64 v15, s[4:5], 0, v15, s[4:5]
	global_load_dword v21, v[14:15], off
	s_waitcnt vmcnt(0)
; #define LAS __attribute__((address_space(3)))
; __device__ __forceinline__ void transpose_item(const float* W, int K, int N, int NP, bf16* WT, LAS float* scr, int item, int lane, const LAS float* tab, long long* bias, int ldb, const float* kscale = nullptr) {
;     ...
;     for (int i = 0; i < 32; ++i) { if (!okn) wv_[i] = 0.f; if (kscale != nullptr) wv_[i] *= kscale[k0 + 2 * i + (lane >> 5)]; scr[(2 * i + (lane >> 5)) * 33 + (lane & 31)] = wv_[i]; }
;     if (tab != nullptr) {
;         const LAS float* tp = tab + k0 + (lane >> 5);
; #pragma unroll
;         for (int bp = 0; bp < 5; ++bp) { float s = 0.f;
; #pragma unroll
;             for (int i = 0; i < 32; ++i) s += tp[bp * 2048 + 2 * i] * wv_[i];
;             s += __shfl_xor(s, 32);
;             if (lane < 32) atomicAdd((unsigned long long*)(bias + (size_t)bp * ldb + n), (unsigned long long)(long long)(s * 4294967296.f)); }
	v_cndmask_b32_e32 v52, 0, v7, vcc
	v_cndmask_b32_e32 v56, 0, v42, vcc
	v_cndmask_b32_e32 v57, 0, v41, vcc
	v_cndmask_b32_e32 v58, 0, v40, vcc
	v_cndmask_b32_e32 v59, 0, v39, vcc
	v_cndmask_b32_e32 v53, 0, v45, vcc
	v_cndmask_b32_e32 v54, 0, v44, vcc
	v_cndmask_b32_e32 v55, 0, v43, vcc
	v_cndmask_b32_e32 v43, v55, v43, vcc
	v_cndmask_b32_e32 v44, v54, v44, vcc
	v_cndmask_b32_e32 v45, v53, v45, vcc
	v_cndmask_b32_e32 v42, v56, v42, vcc
	v_cndmask_b32_e32 v41, v57, v41, vcc
	v_cndmask_b32_e32 v40, v58, v40, vcc
	v_cndmask_b32_e32 v39, v59, v39, vcc
	v_cndmask_b32_e32 v60, 0, v38, vcc
	v_cndmask_b32_e32 v61, 0, v37, vcc
	v_cndmask_b32_e32 v62, 0, v36, vcc
	v_cndmask_b32_e32 v63, 0, v35, vcc
	v_cndmask_b32_e32 v64, 0, v34, vcc
	v_cndmask_b32_e32 v65, 0, v32, vcc
	v_cndmask_b32_e32 v31, 0, v46, vcc
	v_cndmask_b32_e32 v66, 0, v47, vcc
	v_add_u32_e32 v14, 0x400, v13
	ds_write2_b32 v14, v56, v57 offset0:8 offset1:74
	ds_write2_b32 v14, v58, v59 offset0:140 offset1:206
	v_add_u32_e32 v14, 0x800, v13
	ds_write2_b32 v14, v60, v61 offset0:16 offset1:82
	ds_write2_b32 v14, v62, v63 offset0:148 offset1:214
	v_add_u32_e32 v14, 0xc00, v13
	ds_write2_b32 v14, v64, v65 offset0:24 offset1:90
	ds_write2_b32 v14, v31, v66 offset0:156 offset1:222
	v_add_u32_e32 v14, 0x1000, v13
	s_and_b32 s4, s22, 0xffffff00
	ds_write2_b32 v13, v52, v53 offset1:66
	ds_write2_b32 v13, v54, v55 offset0:132 offset1:198
	v_cndmask_b32_e32 v31, v31, v46, vcc
	v_cndmask_b32_e32 v46, v52, v7, vcc
	v_cndmask_b32_e32 v38, v60, v38, vcc
	v_cndmask_b32_e32 v37, v61, v37, vcc
	v_cndmask_b32_e32 v36, v62, v36, vcc
	v_cndmask_b32_e32 v35, v63, v35, vcc
	v_cndmask_b32_e32 v34, v64, v34, vcc
	v_cndmask_b32_e32 v32, v65, v32, vcc
	v_ashrrev_i32_e32 v7, 31, v6
	s_waitcnt vmcnt(15)
	v_cndmask_b32_e32 v67, 0, v48, vcc
	s_waitcnt vmcnt(14)
	v_cndmask_b32_e32 v68, 0, v49, vcc
	s_waitcnt vmcnt(13)
	v_cndmask_b32_e32 v69, 0, v50, vcc
	s_waitcnt vmcnt(12)
	v_cndmask_b32_e32 v70, 0, v51, vcc
	ds_write2_b32 v14, v67, v68 offset0:32 offset1:98
	ds_write2_b32 v14, v69, v70 offset0:164 offset1:230
	s_waitcnt vmcnt(11)
	v_cndmask_b32_e32 v71, 0, v25, vcc
	s_waitcnt vmcnt(10)
	v_cndmask_b32_e32 v72, 0, v24, vcc
	v_add_u32_e32 v14, 0x1400, v13
	s_waitcnt vmcnt(9)
	v_cndmask_b32_e32 v23, 0, v26, vcc
	s_waitcnt vmcnt(8)
	v_cndmask_b32_e32 v22, 0, v27, vcc
	ds_write2_b32 v14, v71, v72 offset0:40 offset1:106
	ds_write2_b32 v14, v23, v22 offset0:172 offset1:238
	v_add_u32_e32 v14, 0x1800, v13
	v_cndmask_b32_e32 v22, v22, v27, vcc
	v_cndmask_b32_e32 v23, v23, v26, vcc
	v_cndmask_b32_e32 v26, v70, v51, vcc
	v_cndmask_b32_e32 v27, v69, v50, vcc
	v_cndmask_b32_e32 v25, v71, v25, vcc
	s_waitcnt vmcnt(7)
	v_cndmask_b32_e32 v73, 0, v28, vcc
	s_waitcnt vmcnt(6)
	v_cndmask_b32_e32 v74, 0, v29, vcc
	ds_write2_b32 v14, v73, v74 offset0:48 offset1:114
	v_cndmask_b32_e32 v24, v72, v24, vcc
	v_lshl_add_u64 v[6:7], v[6:7], 3, s[14:15]
	s_waitcnt vmcnt(5)
	v_cndmask_b32_e32 v75, 0, v30, vcc
	s_waitcnt vmcnt(4)
	v_cndmask_b32_e32 v17, 0, v18, vcc
	s_waitcnt vmcnt(3)
	v_cndmask_b32_e32 v76, 0, v19, vcc
	s_waitcnt vmcnt(2)
	v_cndmask_b32_e32 v15, 0, v20, vcc
	ds_write2_b32 v14, v75, v17 offset0:180 offset1:246
	ds_write2_b32 v77, v76, v15 offset0:56 offset1:122
	v_cndmask_b32_e32 v17, v17, v18, vcc
	v_cndmask_b32_e32 v18, v75, v30, vcc
	v_cndmask_b32_e32 v30, v66, v47, vcc
	v_add_u32_e32 v47, s4, v8
	v_cndmask_b32_e32 v15, v15, v20, vcc
	v_cndmask_b32_e32 v20, v73, v28, vcc
	s_waitcnt vmcnt(1)
	v_cndmask_b32_e32 v78, 0, v16, vcc
	v_cndmask_b32_e32 v14, v78, v16, vcc
	v_cndmask_b32_e32 v16, v76, v19, vcc
	s_waitcnt vmcnt(0)
	v_cndmask_b32_e32 v21, 0, v21, vcc
	ds_write2_b32 v77, v78, v21 offset0:188 offset1:254
	v_cndmask_b32_e32 v19, v74, v29, vcc
	v_cndmask_b32_e32 v28, v68, v49, vcc
	v_cndmask_b32_e32 v29, v67, v48, vcc
	ds_read2_b32 v[48:49], v47 offset1:2
	ds_read2_b32 v[50:51], v47 offset0:4 offset1:6
	ds_read2_b32 v[52:53], v47 offset0:8 offset1:10
	ds_read2_b32 v[54:55], v47 offset0:12 offset1:14
	s_waitcnt lgkmcnt(3)
	v_fma_f32 v48, v48, v46, 0
	v_fmac_f32_e32 v48, v49, v45
	s_waitcnt lgkmcnt(2)
	v_fmac_f32_e32 v48, v50, v44
	v_fmac_f32_e32 v48, v51, v43
	ds_read2_b32 v[50:51], v47 offset0:16 offset1:18
	s_waitcnt lgkmcnt(2)
	v_fmac_f32_e32 v48, v52, v42
	v_fmac_f32_e32 v48, v53, v41
	ds_read2_b32 v[52:53], v47 offset0:20 offset1:22
	s_waitcnt lgkmcnt(2)
	v_fmac_f32_e32 v48, v54, v40
	v_fmac_f32_e32 v48, v55, v39
	ds_read2_b32 v[54:55], v47 offset0:24 offset1:26
	s_waitcnt lgkmcnt(2)
	v_fmac_f32_e32 v48, v50, v38
	v_fmac_f32_e32 v48, v51, v37
	ds_read2_b32 v[50:51], v47 offset0:28 offset1:30
	s_waitcnt lgkmcnt(2)
	v_fmac_f32_e32 v48, v52, v36
	v_fmac_f32_e32 v48, v53, v35
	ds_read2_b32 v[52:53], v47 offset0:32 offset1:34
	s_waitcnt lgkmcnt(2)
	v_fmac_f32_e32 v48, v54, v34
	v_fmac_f32_e32 v48, v55, v32
	ds_read2_b32 v[54:55], v47 offset0:36 offset1:38
	s_waitcnt lgkmcnt(2)
	v_fmac_f32_e32 v48, v50, v31
	v_fmac_f32_e32 v48, v51, v30
	ds_read2_b32 v[50:51], v47 offset0:40 offset1:42
	s_waitcnt lgkmcnt(2)
	v_fmac_f32_e32 v48, v52, v29
	v_fmac_f32_e32 v48, v53, v28
	ds_read2_b32 v[52:53], v47 offset0:44 offset1:46
	s_waitcnt lgkmcnt(2)
	v_fmac_f32_e32 v48, v54, v27
	v_fmac_f32_e32 v48, v55, v26
	ds_read2_b32 v[54:55], v47 offset0:48 offset1:50
	s_waitcnt lgkmcnt(2)
	v_fmac_f32_e32 v48, v50, v25
	v_fmac_f32_e32 v48, v51, v24
	ds_read2_b32 v[50:51], v47 offset0:52 offset1:54
	s_waitcnt lgkmcnt(2)
	v_fmac_f32_e32 v48, v52, v23
	v_fmac_f32_e32 v48, v53, v22
	ds_read2_b32 v[52:53], v47 offset0:56 offset1:58
	s_waitcnt lgkmcnt(2)
	v_fmac_f32_e32 v48, v54, v20
	v_fmac_f32_e32 v48, v55, v19
	ds_read2_b32 v[54:55], v47 offset0:60 offset1:62
	s_waitcnt lgkmcnt(2)
	v_fmac_f32_e32 v48, v50, v18
	v_fmac_f32_e32 v48, v51, v17
	s_waitcnt lgkmcnt(1)
	v_fmac_f32_e32 v48, v52, v16
	v_fmac_f32_e32 v48, v53, v15
	s_waitcnt lgkmcnt(0)
	v_fmac_f32_e32 v48, v54, v14
	v_fmac_f32_e32 v48, v55, v21
	ds_bpermute_b32 v49, v9, v48
	s_and_saveexec_b64 s[4:5], s[2:3]
	s_cbranch_execz .LBB0_104
	s_waitcnt lgkmcnt(0)
	v_add_f32_e32 v48, v48, v49
	v_mul_f32_e32 v48, 0x4f800000, v48
	v_trunc_f32_e32 v48, v48
	v_mul_f32_e64 v49, |v48|, s97
	v_floor_f32_e32 v49, v49
	v_fma_f32 v50, v49, s74, |v48|
	v_cvt_u32_f32_e32 v50, v50
	v_cvt_u32_f32_e32 v49, v49
	v_ashrrev_i32_e32 v51, 31, v48
	v_xor_b32_e32 v48, v50, v51
	v_xor_b32_e32 v49, v49, v51
	v_sub_co_u32_e32 v48, vcc, v48, v51
	s_nop 1
	v_subb_co_u32_e32 v49, vcc, v49, v51, vcc
	global_atomic_add_x2 v[6:7], v[48:49], off

; __device__ __forceinline__ void transpose_item(const float* W, int K, int N, int NP, bf16* WT, LAS float* scr, int item, int lane, const LAS float* tab, long long* bias, int ldb, const float* kscale = nullptr) {
;     const int nblk = NP / 32, kb = item / nblk, nb = item - kb * nblk, k0 = 64 * kb, n0 = 32 * nb;
;     const int n = n0 + (lane & 31); const bool okn = n < N;
;     float wv_[32];
;     const float* wp = W + (size_t)(k0 + (lane >> 5)) * N + (okn ? n : 0);
; #pragma unroll
;     for (int i = 0; i < 32; ++i) wv_[i] = wp[(size_t)(2 * i) * N];
; #pragma unroll
;     for (int i = 0; i < 32; ++i) { if (!okn) wv_[i] = 0.f; if (kscale != nullptr) wv_[i] *= kscale[k0 + 2 * i + (lane >> 5)]; scr[(2 * i + (lane >> 5)) * 33 + (lane & 31)] = wv_[i]; }
.LBB0_117:
	s_ashr_i32 s4, s16, 31
	s_lshr_b32 s4, s4, 24
	s_add_i32 s18, s16, s4
	s_ashr_i32 s4, s18, 8
	s_lshl_b32 s15, s4, 13
	s_lshl_b32 s14, s4, 6
	s_sub_i32 s4, s17, s15
	v_add_u32_e32 v6, s4, v12
	v_or_b32_e32 v14, s14, v3
	v_ashrrev_i32_e32 v15, 31, v14
	v_cmp_gt_i32_e32 vcc, s93, v6
	v_lshlrev_b64 v[14:15], 15, v[14:15]
	v_lshl_add_u64 v[14:15], s[6:7], 0, v[14:15]
	v_cndmask_b32_e32 v16, 0, v6, vcc
	v_ashrrev_i32_e32 v17, 31, v16
	v_lshl_add_u64 v[14:15], v[16:17], 2, v[14:15]
	v_add_co_u32_e64 v16, s[4:5], s92, v14
	v_add_u32_e32 v77, 0x1c00, v13
	s_nop 0
	v_addc_co_u32_e64 v17, s[4:5], 0, v15, s[4:5]
	v_add_co_u32_e64 v18, s[4:5], s78, v14
	s_nop 1
	v_addc_co_u32_e64 v19, s[4:5], 0, v15, s[4:5]
	v_add_co_u32_e64 v20, s[4:5], s49, v14
	s_nop 1
	v_addc_co_u32_e64 v21, s[4:5], 0, v15, s[4:5]
	v_add_co_u32_e64 v22, s[4:5], s79, v14
	s_nop 1
	v_addc_co_u32_e64 v23, s[4:5], 0, v15, s[4:5]
	v_add_co_u32_e64 v24, s[4:5], s0, v14
	s_nop 1
	v_addc_co_u32_e64 v25, s[4:5], 0, v15, s[4:5]
	v_add_co_u32_e64 v26, s[4:5], s40, v14
	s_nop 1
	v_addc_co_u32_e64 v27, s[4:5], 0, v15, s[4:5]
	v_add_co_u32_e64 v28, s[4:5], s96, v14
	s_nop 1
	v_addc_co_u32_e64 v29, s[4:5], 0, v15, s[4:5]
	global_load_dword v7, v[14:15], off
	global_load_dword v45, v[16:17], off
	global_load_dword v44, v[18:19], off
	global_load_dword v43, v[20:21], off
	global_load_dword v42, v[22:23], off
	global_load_dword v41, v[24:25], off
	global_load_dword v40, v[26:27], off
	global_load_dword v39, v[28:29], off
	v_add_co_u32_e64 v16, s[4:5], s22, v14
	s_nop 1
	v_addc_co_u32_e64 v17, s[4:5], 0, v15, s[4:5]
	s_mov_b32 s4, 0x90000
	s_nop 0
	v_add_co_u32_e64 v18, s[4:5], s4, v14
	s_nop 1
	v_addc_co_u32_e64 v19, s[4:5], 0, v15, s[4:5]
	s_mov_b32 s4, 0xa0000
	s_nop 0
	v_add_co_u32_e64 v20, s[4:5], s4, v14
	s_nop 1
	v_addc_co_u32_e64 v21, s[4:5], 0, v15, s[4:5]
	s_mov_b32 s4, 0xb0000
	s_nop 0
	v_add_co_u32_e64 v22, s[4:5], s4, v14
	s_nop 1
	v_addc_co_u32_e64 v23, s[4:5], 0, v15, s[4:5]
	s_mov_b32 s4, 0xc0000
	s_nop 0
	v_add_co_u32_e64 v24, s[4:5], s4, v14
	s_nop 1
	v_addc_co_u32_e64 v25, s[4:5], 0, v15, s[4:5]
	s_mov_b32 s4, 0xd0000
	s_nop 0
	v_add_co_u32_e64 v26, s[4:5], s4, v14
	s_nop 0
	s_nop 0
	v_addc_co_u32_e64 v27, s[4:5], 0, v15, s[4:5]
	s_mov_b32 s4, 0xe0000
	s_nop 0
	v_add_co_u32_e64 v28, s[4:5], s4, v14
	s_nop 0
	s_nop 0
	v_addc_co_u32_e64 v29, s[4:5], 0, v15, s[4:5]
	s_mov_b32 s4, 0xf0000
	s_nop 0
	v_add_co_u32_e64 v30, s[4:5], s4, v14
	s_nop 0
	s_nop 0
	v_addc_co_u32_e64 v31, s[4:5], 0, v15, s[4:5]
	s_mov_b32 s4, 0x100000
	global_load_dword v38, v[16:17], off
	global_load_dword v37, v[18:19], off
	global_load_dword v36, v[20:21], off
	global_load_dword v35, v[22:23], off
	global_load_dword v34, v[24:25], off
	global_load_dword v32, v[26:27], off
	global_load_dword v46, v[28:29], off
	global_load_dword v47, v[30:31], off
	v_add_co_u32_e64 v16, s[4:5], s4, v14
	s_nop 0
	s_nop 0
	v_addc_co_u32_e64 v17, s[4:5], 0, v15, s[4:5]
	s_mov_b32 s4, 0x110000
	s_nop 0
	v_add_co_u32_e64 v18, s[4:5], s4, v14
	s_nop 0
	s_nop 0
	v_addc_co_u32_e64 v19, s[4:5], 0, v15, s[4:5]
	s_mov_b32 s4, 0x120000
	s_nop 0
	v_add_co_u32_e64 v20, s[4:5], s4, v14
	s_nop 0
	s_nop 0
	v_addc_co_u32_e64 v21, s[4:5], 0, v15, s[4:5]
	s_mov_b32 s4, 0x130000
	s_nop 0
	v_add_co_u32_e64 v22, s[4:5], s4, v14
	s_nop 0
	s_nop 0
	v_addc_co_u32_e64 v23, s[4:5], 0, v15, s[4:5]
	s_mov_b32 s4, 0x140000
	s_nop 0
	v_add_co_u32_e64 v24, s[4:5], s4, v14
	s_nop 0
	s_nop 0
	v_addc_co_u32_e64 v25, s[4:5], 0, v15, s[4:5]
	s_mov_b32 s4, 0x150000
	s_nop 0
	v_add_co_u32_e64 v26, s[4:5], s4, v14
	s_nop 0
	s_nop 0
	v_addc_co_u32_e64 v27, s[4:5], 0, v15, s[4:5]
	s_mov_b32 s4, 0x160000
	s_nop 0
	v_add_co_u32_e64 v28, s[4:5], s4, v14
	s_nop 0
	s_nop 0
	v_addc_co_u32_e64 v29, s[4:5], 0, v15, s[4:5]
	s_mov_b32 s4, 0x170000
	s_nop 0
	v_add_co_u32_e64 v30, s[4:5], s4, v14
	s_nop 1
	v_addc_co_u32_e64 v31, s[4:5], 0, v15, s[4:5]
	s_mov_b32 s4, 0x180000
	global_load_dword v48, v[16:17], off
	global_load_dword v49, v[18:19], off
	global_load_dword v50, v[20:21], off
	global_load_dword v51, v[22:23], off
	s_nop 0
	global_load_dword v25, v[24:25], off
	s_nop 0
	global_load_dword v24, v[26:27], off
	s_nop 0
	global_load_dword v26, v[28:29], off
	global_load_dword v27, v[30:31], off
	v_add_co_u32_e64 v16, s[4:5], s4, v14
	s_nop 1
	v_addc_co_u32_e64 v17, s[4:5], 0, v15, s[4:5]
	s_mov_b32 s4, 0x190000
	s_nop 0
	v_add_co_u32_e64 v18, s[4:5], s4, v14
	s_nop 1
	v_addc_co_u32_e64 v19, s[4:5], 0, v15, s[4:5]
	s_mov_b32 s4, 0x1a0000
	global_load_dword v28, v[16:17], off
	global_load_dword v29, v[18:19], off
	v_add_co_u32_e64 v16, s[4:5], s4, v14
	s_nop 1
	v_addc_co_u32_e64 v17, s[4:5], 0, v15, s[4:5]
	s_mov_b32 s4, 0x1b0000
	s_nop 0
	v_add_co_u32_e64 v18, s[4:5], s4, v14
	s_nop 1
	v_addc_co_u32_e64 v19, s[4:5], 0, v15, s[4:5]
	s_mov_b32 s4, 0x1c0000
	s_nop 0
	v_add_co_u32_e64 v20, s[4:5], s4, v14
	s_nop 1
	v_addc_co_u32_e64 v21, s[4:5], 0, v15, s[4:5]
	s_mov_b32 s4, 0x1d0000
	s_nop 0
	v_add_co_u32_e64 v22, s[4:5], s4, v14
	s_nop 1
	v_addc_co_u32_e64 v23, s[4:5], 0, v15, s[4:5]
	s_mov_b32 s4, 0x1e0000
	global_load_dword v30, v[16:17], off
	s_nop 0
	global_load_dword v18, v[18:19], off
	s_nop 0
	global_load_dword v19, v[20:21], off
	s_nop 0
	global_load_dword v20, v[22:23], off
	v_add_co_u32_e64 v16, s[4:5], s4, v14
	s_nop 1
	v_addc_co_u32_e64 v17, s[4:5], 0, v15, s[4:5]
	s_mov_b32 s4, 0x1f0000
	s_nop 0
	v_add_co_u32_e64 v14, s[4:5], s4, v14
	global_load_dword v16, v[16:17], off
	s_nop 0
	v_addc_co_u32_e64 v15, s[4:5], 0, v15, s[4:5]
	global_load_dword v21, v[14:15], off
	s_waitcnt vmcnt(0)
; #define LAS __attribute__((address_space(3)))
; __device__ __forceinline__ void transpose_item(const float* W, int K, int N, int NP, bf16* WT, LAS float* scr, int item, int lane, const LAS float* tab, long long* bias, int ldb, const float* kscale = nullptr) {
;     ...
;     for (int i = 0; i < 32; ++i) { if (!okn) wv_[i] = 0.f; if (kscale != nullptr) wv_[i] *= kscale[k0 + 2 * i + (lane >> 5)]; scr[(2 * i + (lane >> 5)) * 33 + (lane & 31)] = wv_[i]; }
;     if (tab != nullptr) {
;         const LAS float* tp = tab + k0 + (lane >> 5);
; #pragma unroll
;         for (int bp = 0; bp < 5; ++bp) { float s = 0.f;
; #pragma unroll
;             for (int i = 0; i < 32; ++i) s += tp[bp * 2048 + 2 * i] * wv_[i];
;             s += __shfl_xor(s, 32);
;             if (lane < 32) atomicAdd((unsigned long long*)(bias + (size_t)bp * ldb + n), (unsigned long long)(long long)(s * 4294967296.f)); }
	v_cndmask_b32_e32 v52, 0, v7, vcc
	v_cndmask_b32_e32 v56, 0, v42, vcc
	v_cndmask_b32_e32 v57, 0, v41, vcc
	v_cndmask_b32_e32 v58, 0, v40, vcc
	v_cndmask_b32_e32 v59, 0, v39, vcc
	v_cndmask_b32_e32 v53, 0, v45, vcc
	v_cndmask_b32_e32 v54, 0, v44, vcc
	v_cndmask_b32_e32 v55, 0, v43, vcc
	v_cndmask_b32_e32 v43, v55, v43, vcc
	v_cndmask_b32_e32 v44, v54, v44, vcc
	v_cndmask_b32_e32 v45, v53, v45, vcc
	v_cndmask_b32_e32 v42, v56, v42, vcc
	v_cndmask_b32_e32 v41, v57, v41, vcc
	v_cndmask_b32_e32 v40, v58, v40, vcc
	v_cndmask_b32_e32 v39, v59, v39, vcc
	v_cndmask_b32_e32 v60, 0, v38, vcc
	v_cndmask_b32_e32 v61, 0, v37, vcc
	v_cndmask_b32_e32 v62, 0, v36, vcc
	v_cndmask_b32_e32 v63, 0, v35, vcc
	v_cndmask_b32_e32 v64, 0, v34, vcc
	v_cndmask_b32_e32 v65, 0, v32, vcc
	v_cndmask_b32_e32 v31, 0, v46, vcc
	v_cndmask_b32_e32 v66, 0, v47, vcc
	v_add_u32_e32 v14, 0x400, v13
	ds_write2_b32 v14, v56, v57 offset0:8 offset1:74
	ds_write2_b32 v14, v58, v59 offset0:140 offset1:206
	v_add_u32_e32 v14, 0x800, v13
	ds_write2_b32 v14, v60, v61 offset0:16 offset1:82
	ds_write2_b32 v14, v62, v63 offset0:148 offset1:214
	v_add_u32_e32 v14, 0xc00, v13
	ds_write2_b32 v14, v64, v65 offset0:24 offset1:90
	ds_write2_b32 v14, v31, v66 offset0:156 offset1:222
	v_add_u32_e32 v14, 0x1000, v13
	s_and_b32 s4, s18, 0xffffff00
	ds_write2_b32 v13, v52, v53 offset1:66
	ds_write2_b32 v13, v54, v55 offset0:132 offset1:198
	v_cndmask_b32_e32 v31, v31, v46, vcc
	v_cndmask_b32_e32 v46, v52, v7, vcc
	v_cndmask_b32_e32 v38, v60, v38, vcc
	v_cndmask_b32_e32 v37, v61, v37, vcc
	v_cndmask_b32_e32 v36, v62, v36, vcc
	v_cndmask_b32_e32 v35, v63, v35, vcc
	v_cndmask_b32_e32 v34, v64, v34, vcc
	v_cndmask_b32_e32 v32, v65, v32, vcc
	v_ashrrev_i32_e32 v7, 31, v6
	s_waitcnt vmcnt(15)
	v_cndmask_b32_e32 v67, 0, v48, vcc
	s_waitcnt vmcnt(14)
	v_cndmask_b32_e32 v68, 0, v49, vcc
	s_waitcnt vmcnt(13)
	v_cndmask_b32_e32 v69, 0, v50, vcc
	s_waitcnt vmcnt(12)
	v_cndmask_b32_e32 v70, 0, v51, vcc
	ds_write2_b32 v14, v67, v68 offset0:32 offset1:98
	ds_write2_b32 v14, v69, v70 offset0:164 offset1:230
	s_waitcnt vmcnt(11)
	v_cndmask_b32_e32 v71, 0, v25, vcc
	s_waitcnt vmcnt(10)
	v_cndmask_b32_e32 v72, 0, v24, vcc
	v_add_u32_e32 v14, 0x1400, v13
	s_waitcnt vmcnt(9)
	v_cndmask_b32_e32 v23, 0, v26, vcc
	s_waitcnt vmcnt(8)
	v_cndmask_b32_e32 v22, 0, v27, vcc
	ds_write2_b32 v14, v71, v72 offset0:40 offset1:106
	ds_write2_b32 v14, v23, v22 offset0:172 offset1:238
	v_add_u32_e32 v14, 0x1800, v13
	v_cndmask_b32_e32 v22, v22, v27, vcc
	v_cndmask_b32_e32 v23, v23, v26, vcc
	v_cndmask_b32_e32 v26, v70, v51, vcc
	v_cndmask_b32_e32 v27, v69, v50, vcc
	v_cndmask_b32_e32 v25, v71, v25, vcc
	s_waitcnt vmcnt(7)
	v_cndmask_b32_e32 v73, 0, v28, vcc
	s_waitcnt vmcnt(6)
	v_cndmask_b32_e32 v74, 0, v29, vcc
	ds_write2_b32 v14, v73, v74 offset0:48 offset1:114
	v_cndmask_b32_e32 v24, v72, v24, vcc
	v_lshl_add_u64 v[6:7], v[6:7], 3, s[12:13]
	s_waitcnt vmcnt(5)
	v_cndmask_b32_e32 v75, 0, v30, vcc
	s_waitcnt vmcnt(4)
	v_cndmask_b32_e32 v17, 0, v18, vcc
	s_waitcnt vmcnt(3)
	v_cndmask_b32_e32 v76, 0, v19, vcc
	s_waitcnt vmcnt(2)
	v_cndmask_b32_e32 v15, 0, v20, vcc
	ds_write2_b32 v14, v75, v17 offset0:180 offset1:246
	ds_write2_b32 v77, v76, v15 offset0:56 offset1:122
	v_cndmask_b32_e32 v17, v17, v18, vcc
	v_cndmask_b32_e32 v18, v75, v30, vcc
	v_cndmask_b32_e32 v30, v66, v47, vcc
	v_add_u32_e32 v47, s4, v8
	v_cndmask_b32_e32 v15, v15, v20, vcc
	v_cndmask_b32_e32 v20, v73, v28, vcc
	s_waitcnt vmcnt(1)
	v_cndmask_b32_e32 v78, 0, v16, vcc
	v_cndmask_b32_e32 v14, v78, v16, vcc
	v_cndmask_b32_e32 v16, v76, v19, vcc
	s_waitcnt vmcnt(0)
	v_cndmask_b32_e32 v21, 0, v21, vcc
	ds_write2_b32 v77, v78, v21 offset0:188 offset1:254
	v_cndmask_b32_e32 v19, v74, v29, vcc
	v_cndmask_b32_e32 v28, v68, v49, vcc
	v_cndmask_b32_e32 v29, v67, v48, vcc
	ds_read2_b32 v[48:49], v47 offset1:2
	ds_read2_b32 v[50:51], v47 offset0:4 offset1:6
	ds_read2_b32 v[52:53], v47 offset0:8 offset1:10
	ds_read2_b32 v[54:55], v47 offset0:12 offset1:14
	s_waitcnt lgkmcnt(3)
	v_fma_f32 v48, v48, v46, 0
	v_fmac_f32_e32 v48, v49, v45
	s_waitcnt lgkmcnt(2)
	v_fmac_f32_e32 v48, v50, v44
	v_fmac_f32_e32 v48, v51, v43
	ds_read2_b32 v[50:51], v47 offset0:16 offset1:18
	s_waitcnt lgkmcnt(2)
	v_fmac_f32_e32 v48, v52, v42
	v_fmac_f32_e32 v48, v53, v41
	ds_read2_b32 v[52:53], v47 offset0:20 offset1:22
	s_waitcnt lgkmcnt(2)
	v_fmac_f32_e32 v48, v54, v40
	v_fmac_f32_e32 v48, v55, v39
	ds_read2_b32 v[54:55], v47 offset0:24 offset1:26
	s_waitcnt lgkmcnt(2)
	v_fmac_f32_e32 v48, v50, v38
	v_fmac_f32_e32 v48, v51, v37
	ds_read2_b32 v[50:51], v47 offset0:28 offset1:30
	s_waitcnt lgkmcnt(2)
	v_fmac_f32_e32 v48, v52, v36
	v_fmac_f32_e32 v48, v53, v35
	ds_read2_b32 v[52:53], v47 offset0:32 offset1:34
	s_waitcnt lgkmcnt(2)
	v_fmac_f32_e32 v48, v54, v34
	v_fmac_f32_e32 v48, v55, v32
	ds_read2_b32 v[54:55], v47 offset0:36 offset1:38
	s_waitcnt lgkmcnt(2)
	v_fmac_f32_e32 v48, v50, v31
	v_fmac_f32_e32 v48, v51, v30
	ds_read2_b32 v[50:51], v47 offset0:40 offset1:42
	s_waitcnt lgkmcnt(2)
	v_fmac_f32_e32 v48, v52, v29
	v_fmac_f32_e32 v48, v53, v28
	ds_read2_b32 v[52:53], v47 offset0:44 offset1:46
	s_waitcnt lgkmcnt(2)
	v_fmac_f32_e32 v48, v54, v27
	v_fmac_f32_e32 v48, v55, v26
	ds_read2_b32 v[54:55], v47 offset0:48 offset1:50
	s_waitcnt lgkmcnt(2)
	v_fmac_f32_e32 v48, v50, v25
	v_fmac_f32_e32 v48, v51, v24
	ds_read2_b32 v[50:51], v47 offset0:52 offset1:54
	s_waitcnt lgkmcnt(2)
	v_fmac_f32_e32 v48, v52, v23
	v_fmac_f32_e32 v48, v53, v22
	ds_read2_b32 v[52:53], v47 offset0:56 offset1:58
	s_waitcnt lgkmcnt(2)
	v_fmac_f32_e32 v48, v54, v20
	v_fmac_f32_e32 v48, v55, v19
	ds_read2_b32 v[54:55], v47 offset0:60 offset1:62
	s_waitcnt lgkmcnt(2)
	v_fmac_f32_e32 v48, v50, v18
	v_fmac_f32_e32 v48, v51, v17
	s_waitcnt lgkmcnt(1)
	v_fmac_f32_e32 v48, v52, v16
	v_fmac_f32_e32 v48, v53, v15
	s_waitcnt lgkmcnt(0)
	v_fmac_f32_e32 v48, v54, v14
	v_fmac_f32_e32 v48, v55, v21
	ds_bpermute_b32 v49, v9, v48
	s_and_saveexec_b64 s[4:5], s[2:3]
	s_cbranch_execz .LBB0_119
	s_waitcnt lgkmcnt(0)
	v_add_f32_e32 v48, v48, v49
	v_mul_f32_e32 v48, 0x4f800000, v48
	v_trunc_f32_e32 v48, v48
	v_mul_f32_e64 v49, |v48|, s97
	v_floor_f32_e32 v49, v49
	v_fma_f32 v50, v49, s74, |v48|
	v_cvt_u32_f32_e32 v50, v50
	v_cvt_u32_f32_e32 v49, v49
	v_ashrrev_i32_e32 v51, 31, v48
	v_xor_b32_e32 v48, v50, v51
	v_xor_b32_e32 v49, v49, v51
	v_sub_co_u32_e32 v48, vcc, v48, v51
	s_nop 1
	v_subb_co_u32_e32 v49, vcc, v49, v51, vcc
	global_atomic_add_x2 v[6:7], v[48:49], off

; __device__ __forceinline__ void transpose_item(const float* W, int K, int N, int NP, bf16* WT, LAS float* scr, int item, int lane, const LAS float* tab, long long* bias, int ldb, const float* kscale = nullptr) {
;     const int nblk = NP / 32, kb = item / nblk, nb = item - kb * nblk, k0 = 64 * kb, n0 = 32 * nb;
;     const int n = n0 + (lane & 31); const bool okn = n < N;
;     float wv_[32];
;     const float* wp = W + (size_t)(k0 + (lane >> 5)) * N + (okn ? n : 0);
; #pragma unroll
;     for (int i = 0; i < 32; ++i) wv_[i] = wp[(size_t)(2 * i) * N];
; #pragma unroll
;     for (int i = 0; i < 32; ++i) { if (!okn) wv_[i] = 0.f; if (kscale != nullptr) wv_[i] *= kscale[k0 + 2 * i + (lane >> 5)]; scr[(2 * i + (lane >> 5)) * 33 + (lane & 31)] = wv_[i]; }
.LBB0_471:
	s_ashr_i32 s4, s12, 31
	s_lshr_b32 s4, s4, 24
	s_add_i32 s14, s12, s4
	s_ashr_i32 s4, s14, 8
	s_lshl_b32 s11, s4, 13
	s_lshl_b32 s10, s4, 6
	s_sub_i32 s4, s13, s11
	v_add_u32_e32 v4, s4, v1
	v_or_b32_e32 v6, s10, v8
	v_cmp_gt_i32_e32 vcc, s93, v4
	v_ashrrev_i32_e32 v7, 31, v6
	v_lshlrev_b64 v[6:7], 15, v[6:7]
	v_cndmask_b32_e32 v14, 0, v4, vcc
	v_lshl_add_u64 v[6:7], s[6:7], 0, v[6:7]
	v_ashrrev_i32_e32 v15, 31, v14
	v_lshl_add_u64 v[6:7], v[14:15], 2, v[6:7]
	v_add_co_u32_e64 v14, s[4:5], s92, v6
	global_load_dword v5, v[6:7], off
	s_nop 0
	v_addc_co_u32_e64 v15, s[4:5], 0, v7, s[4:5]
	global_load_dword v43, v[14:15], off
	v_add_co_u32_e64 v14, s[4:5], s78, v6
	v_add_u32_e32 v75, 0x1c00, v13
	s_nop 0
	v_addc_co_u32_e64 v15, s[4:5], 0, v7, s[4:5]
	global_load_dword v42, v[14:15], off
	v_add_co_u32_e64 v14, s[4:5], s49, v6
	s_nop 1
	v_addc_co_u32_e64 v15, s[4:5], 0, v7, s[4:5]
	global_load_dword v41, v[14:15], off
	v_add_co_u32_e64 v14, s[4:5], s79, v6
	s_nop 1
	v_addc_co_u32_e64 v15, s[4:5], 0, v7, s[4:5]
	global_load_dword v40, v[14:15], off
	v_add_co_u32_e64 v14, s[4:5], s0, v6
	s_nop 1
	v_addc_co_u32_e64 v15, s[4:5], 0, v7, s[4:5]
	s_mov_b32 s4, 0x60000
	global_load_dword v39, v[14:15], off
	v_add_co_u32_e64 v14, s[4:5], s4, v6
	s_nop 0
	s_nop 0
	v_addc_co_u32_e64 v15, s[4:5], 0, v7, s[4:5]
	global_load_dword v38, v[14:15], off
	v_add_co_u32_e64 v14, s[4:5], s96, v6
	s_nop 0
	s_nop 0
	v_addc_co_u32_e64 v15, s[4:5], 0, v7, s[4:5]
	s_mov_b32 s4, 0x80000
	global_load_dword v37, v[14:15], off
	v_add_co_u32_e64 v14, s[4:5], s4, v6
	s_nop 0
	s_nop 0
	v_addc_co_u32_e64 v15, s[4:5], 0, v7, s[4:5]
	s_mov_b32 s4, 0x90000
	global_load_dword v36, v[14:15], off
	v_add_co_u32_e64 v14, s[4:5], s4, v6
	s_nop 1
	v_addc_co_u32_e64 v15, s[4:5], 0, v7, s[4:5]
	s_mov_b32 s4, 0xa0000
	global_load_dword v35, v[14:15], off
	v_add_co_u32_e64 v14, s[4:5], s4, v6
	s_nop 1
	v_addc_co_u32_e64 v15, s[4:5], 0, v7, s[4:5]
	s_mov_b32 s4, 0xb0000
	global_load_dword v34, v[14:15], off
	v_add_co_u32_e64 v14, s[4:5], s4, v6
	s_nop 1
	v_addc_co_u32_e64 v15, s[4:5], 0, v7, s[4:5]
	s_mov_b32 s4, 0xc0000
	global_load_dword v32, v[14:15], off
	v_add_co_u32_e64 v14, s[4:5], s4, v6
	s_nop 1
	v_addc_co_u32_e64 v15, s[4:5], 0, v7, s[4:5]
	s_mov_b32 s4, 0xd0000
	global_load_dword v31, v[14:15], off
	v_add_co_u32_e64 v14, s[4:5], s4, v6
	s_nop 1
	v_addc_co_u32_e64 v15, s[4:5], 0, v7, s[4:5]
	s_mov_b32 s4, 0xe0000
	global_load_dword v30, v[14:15], off
	v_add_co_u32_e64 v14, s[4:5], s4, v6
	s_nop 1
	v_addc_co_u32_e64 v15, s[4:5], 0, v7, s[4:5]
	s_mov_b32 s4, 0xf0000
	global_load_dword v29, v[14:15], off
	v_add_co_u32_e64 v14, s[4:5], s4, v6
	s_nop 0
	s_nop 0
	v_addc_co_u32_e64 v15, s[4:5], 0, v7, s[4:5]
	s_mov_b32 s4, 0x100000
	global_load_dword v28, v[14:15], off
	v_add_co_u32_e64 v14, s[4:5], s4, v6
	s_nop 0
	s_nop 0
	v_addc_co_u32_e64 v15, s[4:5], 0, v7, s[4:5]
	s_mov_b32 s4, 0x110000
	global_load_dword v27, v[14:15], off
	v_add_co_u32_e64 v14, s[4:5], s4, v6
	s_nop 0
	s_nop 0
	v_addc_co_u32_e64 v15, s[4:5], 0, v7, s[4:5]
	s_mov_b32 s4, 0x120000
	global_load_dword v26, v[14:15], off
	v_add_co_u32_e64 v14, s[4:5], s4, v6
	s_nop 0
	s_nop 0
	v_addc_co_u32_e64 v15, s[4:5], 0, v7, s[4:5]
	s_mov_b32 s4, 0x130000
	global_load_dword v25, v[14:15], off
	v_add_co_u32_e64 v14, s[4:5], s4, v6
	s_nop 0
	s_nop 0
	v_addc_co_u32_e64 v15, s[4:5], 0, v7, s[4:5]
	s_mov_b32 s4, 0x140000
	global_load_dword v24, v[14:15], off
	v_add_co_u32_e64 v14, s[4:5], s4, v6
	s_nop 0
	s_nop 0
	v_addc_co_u32_e64 v15, s[4:5], 0, v7, s[4:5]
	s_mov_b32 s4, 0x150000
	global_load_dword v23, v[14:15], off
	v_add_co_u32_e64 v14, s[4:5], s4, v6
	s_nop 1
	v_addc_co_u32_e64 v15, s[4:5], 0, v7, s[4:5]
	s_mov_b32 s4, 0x160000
	global_load_dword v22, v[14:15], off
	v_add_co_u32_e64 v14, s[4:5], s4, v6
	s_nop 1
	v_addc_co_u32_e64 v15, s[4:5], 0, v7, s[4:5]
	s_mov_b32 s4, 0x170000
	global_load_dword v21, v[14:15], off
	v_add_co_u32_e64 v14, s[4:5], s4, v6
	s_nop 1
	v_addc_co_u32_e64 v15, s[4:5], 0, v7, s[4:5]
	s_mov_b32 s4, 0x180000
	global_load_dword v20, v[14:15], off
	v_add_co_u32_e64 v14, s[4:5], s4, v6
	s_nop 1
	v_addc_co_u32_e64 v15, s[4:5], 0, v7, s[4:5]
	s_mov_b32 s4, 0x190000
	global_load_dword v19, v[14:15], off
	v_add_co_u32_e64 v14, s[4:5], s4, v6
	s_nop 1
	v_addc_co_u32_e64 v15, s[4:5], 0, v7, s[4:5]
	s_mov_b32 s4, 0x1a0000
	global_load_dword v18, v[14:15], off
	v_add_co_u32_e64 v14, s[4:5], s4, v6
	s_nop 1
	v_addc_co_u32_e64 v15, s[4:5], 0, v7, s[4:5]
	s_mov_b32 s4, 0x1b0000
	global_load_dword v17, v[14:15], off
	v_add_co_u32_e64 v14, s[4:5], s4, v6
	s_nop 1
	v_addc_co_u32_e64 v15, s[4:5], 0, v7, s[4:5]
	s_mov_b32 s4, 0x1c0000
	global_load_dword v16, v[14:15], off
	v_add_co_u32_e64 v14, s[4:5], s4, v6
	s_nop 1
	v_addc_co_u32_e64 v15, s[4:5], 0, v7, s[4:5]
	s_mov_b32 s4, 0x1d0000
	global_load_dword v44, v[14:15], off
	v_add_co_u32_e64 v14, s[4:5], s4, v6
	s_nop 1
	v_addc_co_u32_e64 v15, s[4:5], 0, v7, s[4:5]
	s_mov_b32 s4, 0x1e0000
	global_load_dword v45, v[14:15], off
	v_add_co_u32_e64 v14, s[4:5], s4, v6
	s_nop 1
	v_addc_co_u32_e64 v15, s[4:5], 0, v7, s[4:5]
	s_mov_b32 s4, 0x1f0000
	s_nop 0
	v_add_co_u32_e64 v6, s[4:5], s4, v6
	global_load_dword v14, v[14:15], off
	s_nop 0
	v_addc_co_u32_e64 v7, s[4:5], 0, v7, s[4:5]
	global_load_dword v7, v[6:7], off
	s_waitcnt vmcnt(0)
; #define LAS __attribute__((address_space(3)))
; __device__ __forceinline__ void transpose_item(const float* W, int K, int N, int NP, bf16* WT, LAS float* scr, int item, int lane, const LAS float* tab, long long* bias, int ldb, const float* kscale = nullptr) {
;     ...
;     for (int i = 0; i < 32; ++i) { if (!okn) wv_[i] = 0.f; if (kscale != nullptr) wv_[i] *= kscale[k0 + 2 * i + (lane >> 5)]; scr[(2 * i + (lane >> 5)) * 33 + (lane & 31)] = wv_[i]; }
;     if (tab != nullptr) {
;         const LAS float* tp = tab + k0 + (lane >> 5);
; #pragma unroll
;         for (int bp = 0; bp < 5; ++bp) { float s = 0.f;
; #pragma unroll
;             for (int i = 0; i < 32; ++i) s += tp[bp * 2048 + 2 * i] * wv_[i];
;             s += __shfl_xor(s, 32);
;             if (lane < 32) atomicAdd((unsigned long long*)(bias + (size_t)bp * ldb + n), (unsigned long long)(long long)(s * 4294967296.f)); }
	v_cndmask_b32_e32 v46, 0, v5, vcc
	v_cndmask_b32_e32 v47, 0, v43, vcc
	v_cndmask_b32_e32 v48, 0, v42, vcc
	ds_write2_b32 v13, v46, v47 offset1:66
	v_cndmask_b32_e32 v42, v48, v42, vcc
	v_cndmask_b32_e32 v43, v47, v43, vcc
	v_cndmask_b32_e32 v49, 0, v41, vcc
	v_cndmask_b32_e32 v50, 0, v40, vcc
	v_cndmask_b32_e32 v51, 0, v39, vcc
	v_cndmask_b32_e32 v52, 0, v38, vcc
	v_cndmask_b32_e32 v53, 0, v37, vcc
	v_cndmask_b32_e32 v54, 0, v36, vcc
	ds_write2_b32 v13, v48, v49 offset0:132 offset1:198
	v_cndmask_b32_e32 v37, v53, v37, vcc
	v_cndmask_b32_e32 v38, v52, v38, vcc
	v_cndmask_b32_e32 v39, v51, v39, vcc
	v_cndmask_b32_e32 v40, v50, v40, vcc
	v_cndmask_b32_e32 v41, v49, v41, vcc
	v_cndmask_b32_e32 v55, 0, v35, vcc
	v_cndmask_b32_e32 v56, 0, v34, vcc
	v_cndmask_b32_e32 v57, 0, v32, vcc
	v_cndmask_b32_e32 v58, 0, v31, vcc
	v_cndmask_b32_e32 v59, 0, v30, vcc
	v_cndmask_b32_e32 v60, 0, v29, vcc
	v_cndmask_b32_e32 v61, 0, v28, vcc
	v_cndmask_b32_e32 v62, 0, v27, vcc
	v_cndmask_b32_e32 v63, 0, v26, vcc
	v_cndmask_b32_e32 v64, 0, v25, vcc
	v_add_u32_e32 v6, 0x400, v13
	ds_write2_b32 v6, v50, v51 offset0:8 offset1:74
	ds_write2_b32 v6, v52, v53 offset0:140 offset1:206
	v_add_u32_e32 v6, 0x800, v13
	ds_write2_b32 v6, v54, v55 offset0:16 offset1:82
	ds_write2_b32 v6, v56, v57 offset0:148 offset1:214
	v_add_u32_e32 v6, 0xc00, v13
	ds_write2_b32 v6, v58, v59 offset0:24 offset1:90
	ds_write2_b32 v6, v60, v61 offset0:156 offset1:222
	v_add_u32_e32 v6, 0x1000, v13
	s_waitcnt vmcnt(12)
	v_cndmask_b32_e32 v65, 0, v24, vcc
	ds_write2_b32 v6, v62, v63 offset0:32 offset1:98
	ds_write2_b32 v6, v64, v65 offset0:164 offset1:230
	s_waitcnt vmcnt(11)
	v_cndmask_b32_e32 v66, 0, v23, vcc
	s_waitcnt vmcnt(10)
	v_cndmask_b32_e32 v67, 0, v22, vcc
	v_add_u32_e32 v6, 0x1400, v13
	ds_write2_b32 v6, v66, v67 offset0:40 offset1:106
	s_and_b32 s4, s14, 0xffffff00
	s_waitcnt vmcnt(9)
	v_cndmask_b32_e32 v68, 0, v21, vcc
	v_cndmask_b32_e32 v36, v54, v36, vcc
	v_cndmask_b32_e32 v35, v55, v35, vcc
	v_cndmask_b32_e32 v34, v56, v34, vcc
	v_cndmask_b32_e32 v32, v57, v32, vcc
	v_cndmask_b32_e32 v31, v58, v31, vcc
	v_cndmask_b32_e32 v30, v59, v30, vcc
	s_waitcnt vmcnt(8)
	v_cndmask_b32_e32 v69, 0, v20, vcc
	ds_write2_b32 v6, v68, v69 offset0:172 offset1:238
	v_add_u32_e32 v6, 0x1800, v13
	v_cndmask_b32_e32 v29, v60, v29, vcc
	v_cndmask_b32_e32 v28, v61, v28, vcc
	v_cndmask_b32_e32 v27, v62, v27, vcc
	v_cndmask_b32_e32 v26, v63, v26, vcc
	s_waitcnt vmcnt(7)
	v_cndmask_b32_e32 v70, 0, v19, vcc
	v_cndmask_b32_e32 v25, v64, v25, vcc
	v_cndmask_b32_e32 v24, v65, v24, vcc
	v_cndmask_b32_e32 v23, v66, v23, vcc
	v_cndmask_b32_e32 v22, v67, v22, vcc
	v_cndmask_b32_e32 v21, v68, v21, vcc
	v_cndmask_b32_e32 v20, v69, v20, vcc
	s_waitcnt vmcnt(6)
	v_cndmask_b32_e32 v71, 0, v18, vcc
	ds_write2_b32 v6, v70, v71 offset0:48 offset1:114
	v_cndmask_b32_e32 v19, v70, v19, vcc
	v_cndmask_b32_e32 v18, v71, v18, vcc
	s_waitcnt vmcnt(5)
	v_cndmask_b32_e32 v72, 0, v17, vcc
	v_cndmask_b32_e32 v17, v72, v17, vcc
	s_waitcnt vmcnt(4)
	v_cndmask_b32_e32 v73, 0, v16, vcc
	ds_write2_b32 v6, v72, v73 offset0:180 offset1:246
	v_cndmask_b32_e32 v16, v73, v16, vcc
	s_waitcnt vmcnt(3)
	v_cndmask_b32_e32 v15, 0, v44, vcc
	s_waitcnt vmcnt(2)
	v_cndmask_b32_e32 v74, 0, v45, vcc
	ds_write2_b32 v75, v15, v74 offset0:56 offset1:122
	v_cndmask_b32_e32 v15, v15, v44, vcc
	v_cndmask_b32_e32 v44, v46, v5, vcc
	v_ashrrev_i32_e32 v5, 31, v4
	v_lshl_add_u64 v[4:5], v[4:5], 3, s[8:9]
	s_waitcnt vmcnt(1)
	v_cndmask_b32_e32 v76, 0, v14, vcc
	v_cndmask_b32_e32 v6, v76, v14, vcc
	v_cndmask_b32_e32 v14, v74, v45, vcc
	s_waitcnt vmcnt(0)
	v_cndmask_b32_e32 v7, 0, v7, vcc
	ds_write2_b32 v75, v76, v7 offset0:188 offset1:254
	v_add_u32_e32 v45, s4, v9
	ds_read2_b32 v[46:47], v45 offset1:2
	ds_read2_b32 v[48:49], v45 offset0:4 offset1:6
	ds_read2_b32 v[50:51], v45 offset0:8 offset1:10
	ds_read2_b32 v[52:53], v45 offset0:12 offset1:14
	s_waitcnt lgkmcnt(3)
	v_fma_f32 v46, v46, v44, 0
	v_fmac_f32_e32 v46, v47, v43
	s_waitcnt lgkmcnt(2)
	v_fmac_f32_e32 v46, v48, v42
	v_fmac_f32_e32 v46, v49, v41
	ds_read2_b32 v[48:49], v45 offset0:16 offset1:18
	s_waitcnt lgkmcnt(2)
	v_fmac_f32_e32 v46, v50, v40
	v_fmac_f32_e32 v46, v51, v39
	s_waitcnt lgkmcnt(1)
	v_fmac_f32_e32 v46, v52, v38
	v_fmac_f32_e32 v46, v53, v37
	s_waitcnt lgkmcnt(0)
	v_fmac_f32_e32 v46, v48, v36
	v_fmac_f32_e32 v46, v49, v35
	ds_read2_b32 v[48:49], v45 offset0:20 offset1:22
	s_waitcnt lgkmcnt(0)
	v_fmac_f32_e32 v46, v48, v34
	v_fmac_f32_e32 v46, v49, v32
	ds_read2_b32 v[48:49], v45 offset0:24 offset1:26
	s_waitcnt lgkmcnt(0)
	v_fmac_f32_e32 v46, v48, v31
	v_fmac_f32_e32 v46, v49, v30
	ds_read2_b32 v[48:49], v45 offset0:28 offset1:30
	s_waitcnt lgkmcnt(0)
	v_fmac_f32_e32 v46, v48, v29
	v_fmac_f32_e32 v46, v49, v28
	ds_read2_b32 v[48:49], v45 offset0:32 offset1:34
	s_waitcnt lgkmcnt(0)
	v_fmac_f32_e32 v46, v48, v27
	v_fmac_f32_e32 v46, v49, v26
	ds_read2_b32 v[48:49], v45 offset0:36 offset1:38
	s_waitcnt lgkmcnt(0)
	v_fmac_f32_e32 v46, v48, v25
	v_fmac_f32_e32 v46, v49, v24
	ds_read2_b32 v[48:49], v45 offset0:40 offset1:42
	s_waitcnt lgkmcnt(0)
	v_fmac_f32_e32 v46, v48, v23
	v_fmac_f32_e32 v46, v49, v22
	ds_read2_b32 v[48:49], v45 offset0:44 offset1:46
	s_waitcnt lgkmcnt(0)
	v_fmac_f32_e32 v46, v48, v21
	v_fmac_f32_e32 v46, v49, v20
	ds_read2_b32 v[48:49], v45 offset0:48 offset1:50
	s_waitcnt lgkmcnt(0)
	v_fmac_f32_e32 v46, v48, v19
	v_fmac_f32_e32 v46, v49, v18
	ds_read2_b32 v[48:49], v45 offset0:52 offset1:54
	s_waitcnt lgkmcnt(0)
	v_fmac_f32_e32 v46, v48, v17
	v_fmac_f32_e32 v46, v49, v16
	ds_read2_b32 v[48:49], v45 offset0:56 offset1:58
	s_waitcnt lgkmcnt(0)
	v_fmac_f32_e32 v46, v48, v15
	v_fmac_f32_e32 v46, v49, v14
	ds_read2_b32 v[48:49], v45 offset0:60 offset1:62
	s_waitcnt lgkmcnt(0)
	v_fmac_f32_e32 v46, v48, v6
	v_fmac_f32_e32 v46, v49, v7
	ds_bpermute_b32 v47, v10, v46
	s_and_saveexec_b64 s[4:5], s[2:3]
	s_cbranch_execz .LBB0_473
	s_waitcnt lgkmcnt(0)
	v_add_f32_e32 v46, v46, v47
	v_mul_f32_e32 v46, 0x4f800000, v46
	v_trunc_f32_e32 v46, v46
	v_mul_f32_e64 v47, |v46|, s97
	v_floor_f32_e32 v47, v47
	v_fma_f32 v48, v47, s74, |v46|
	v_cvt_u32_f32_e32 v48, v48
	v_cvt_u32_f32_e32 v47, v47
	v_ashrrev_i32_e32 v49, 31, v46
	v_xor_b32_e32 v46, v48, v49
	v_xor_b32_e32 v47, v47, v49
	v_sub_co_u32_e32 v46, vcc, v46, v49
	s_nop 1
	v_subb_co_u32_e32 v47, vcc, v47, v49, vcc
	global_atomic_add_x2 v[4:5], v[46:47], off

; __device__ __forceinline__ void transpose_item(const float* W, int K, int N, int NP, bf16* WT, LAS float* scr, int item, int lane, const LAS float* tab, long long* bias, int ldb, const float* kscale = nullptr) {
;     const int nblk = NP / 32, kb = item / nblk, nb = item - kb * nblk, k0 = 64 * kb, n0 = 32 * nb;
;     const int n = n0 + (lane & 31); const bool okn = n < N;
;     float wv_[32];
;     const float* wp = W + (size_t)(k0 + (lane >> 5)) * N + (okn ? n : 0);
; #pragma unroll
;     for (int i = 0; i < 32; ++i) wv_[i] = wp[(size_t)(2 * i) * N];
; #pragma unroll
;     for (int i = 0; i < 32; ++i) { if (!okn) wv_[i] = 0.f; if (kscale != nullptr) wv_[i] *= kscale[k0 + 2 * i + (lane >> 5)]; scr[(2 * i + (lane >> 5)) * 33 + (lane & 31)] = wv_[i]; }
.LBB0_1355:
	s_ashr_i32 s3, s15, 31
	s_lshr_b32 s3, s3, 24
	s_add_i32 s13, s15, s3
	s_ashr_i32 s3, s13, 8
	s_lshl_b32 s12, s3, 6
	s_lshl_b32 s3, s3, 13
	s_sub_i32 s6, s16, s3
	v_add_u32_e32 v4, s6, v16
	v_or_b32_e32 v6, s12, v1
	v_cmp_gt_i32_e32 vcc, s93, v4
	v_ashrrev_i32_e32 v7, 31, v6
	v_lshlrev_b64 v[6:7], 15, v[6:7]
	v_cndmask_b32_e32 v18, 0, v4, vcc
	v_lshl_add_u64 v[6:7], s[8:9], 0, v[6:7]
	v_ashrrev_i32_e32 v19, 31, v18
	v_lshl_add_u64 v[6:7], v[18:19], 2, v[6:7]
	v_add_co_u32_e64 v18, s[6:7], s92, v6
	global_load_dword v5, v[6:7], off
	s_nop 0
	v_addc_co_u32_e64 v19, s[6:7], 0, v7, s[6:7]
	global_load_dword v47, v[18:19], off
	v_add_co_u32_e64 v18, s[6:7], s78, v6
	v_add_u32_e32 v79, 0x1c00, v17
	s_nop 0
	v_addc_co_u32_e64 v19, s[6:7], 0, v7, s[6:7]
	global_load_dword v46, v[18:19], off
	v_add_co_u32_e64 v18, s[6:7], s49, v6
	s_nop 1
	v_addc_co_u32_e64 v19, s[6:7], 0, v7, s[6:7]
	global_load_dword v45, v[18:19], off
	v_add_co_u32_e64 v18, s[6:7], s79, v6
	s_nop 1
	v_addc_co_u32_e64 v19, s[6:7], 0, v7, s[6:7]
	global_load_dword v44, v[18:19], off
	v_add_co_u32_e64 v18, s[6:7], s0, v6
	s_nop 1
	v_addc_co_u32_e64 v19, s[6:7], 0, v7, s[6:7]
	global_load_dword v43, v[18:19], off
	v_add_co_u32_e64 v18, s[6:7], s40, v6
	s_nop 0
	s_nop 0
	v_addc_co_u32_e64 v19, s[6:7], 0, v7, s[6:7]
	global_load_dword v42, v[18:19], off
	v_add_co_u32_e64 v18, s[6:7], s96, v6
	s_nop 0
	s_nop 0
	v_addc_co_u32_e64 v19, s[6:7], 0, v7, s[6:7]
	s_mov_b32 s6, 0x80000
	global_load_dword v41, v[18:19], off
	v_add_co_u32_e64 v18, s[6:7], s6, v6
	s_nop 0
	s_nop 0
	v_addc_co_u32_e64 v19, s[6:7], 0, v7, s[6:7]
	s_mov_b32 s6, 0x90000
	global_load_dword v40, v[18:19], off
	v_add_co_u32_e64 v18, s[6:7], s6, v6
	s_nop 1
	v_addc_co_u32_e64 v19, s[6:7], 0, v7, s[6:7]
	s_mov_b32 s6, 0xa0000
	global_load_dword v39, v[18:19], off
	v_add_co_u32_e64 v18, s[6:7], s6, v6
	s_nop 1
	v_addc_co_u32_e64 v19, s[6:7], 0, v7, s[6:7]
	s_mov_b32 s6, 0xb0000
	global_load_dword v38, v[18:19], off
	v_add_co_u32_e64 v18, s[6:7], s6, v6
	s_nop 1
	v_addc_co_u32_e64 v19, s[6:7], 0, v7, s[6:7]
	s_mov_b32 s6, 0xc0000
	global_load_dword v37, v[18:19], off
	v_add_co_u32_e64 v18, s[6:7], s6, v6
	s_nop 1
	v_addc_co_u32_e64 v19, s[6:7], 0, v7, s[6:7]
	s_mov_b32 s6, 0xd0000
	global_load_dword v36, v[18:19], off
	v_add_co_u32_e64 v18, s[6:7], s6, v6
	s_nop 1
	v_addc_co_u32_e64 v19, s[6:7], 0, v7, s[6:7]
	s_mov_b32 s6, 0xe0000
	global_load_dword v35, v[18:19], off
	v_add_co_u32_e64 v18, s[6:7], s6, v6
	s_nop 1
	v_addc_co_u32_e64 v19, s[6:7], 0, v7, s[6:7]
	s_mov_b32 s6, 0xf0000
	global_load_dword v34, v[18:19], off
	v_add_co_u32_e64 v18, s[6:7], s6, v6
	s_nop 0
	s_nop 0
	v_addc_co_u32_e64 v19, s[6:7], 0, v7, s[6:7]
	s_mov_b32 s6, 0x100000
	global_load_dword v32, v[18:19], off
	v_add_co_u32_e64 v18, s[6:7], s6, v6
	s_nop 0
	s_nop 0
	v_addc_co_u32_e64 v19, s[6:7], 0, v7, s[6:7]
	s_mov_b32 s6, 0x110000
	global_load_dword v31, v[18:19], off
	v_add_co_u32_e64 v18, s[6:7], s6, v6
	s_nop 0
	s_nop 0
	v_addc_co_u32_e64 v19, s[6:7], 0, v7, s[6:7]
	s_mov_b32 s6, 0x120000
	global_load_dword v30, v[18:19], off
	v_add_co_u32_e64 v18, s[6:7], s6, v6
	s_nop 0
	s_nop 0
	v_addc_co_u32_e64 v19, s[6:7], 0, v7, s[6:7]
	s_mov_b32 s6, 0x130000
	global_load_dword v29, v[18:19], off
	v_add_co_u32_e64 v18, s[6:7], s6, v6
	s_nop 0
	s_nop 0
	v_addc_co_u32_e64 v19, s[6:7], 0, v7, s[6:7]
	s_mov_b32 s6, 0x140000
	global_load_dword v28, v[18:19], off
	v_add_co_u32_e64 v18, s[6:7], s6, v6
	s_nop 0
	s_nop 0
	v_addc_co_u32_e64 v19, s[6:7], 0, v7, s[6:7]
	s_mov_b32 s6, 0x150000
	global_load_dword v27, v[18:19], off
	v_add_co_u32_e64 v18, s[6:7], s6, v6
	s_nop 1
	v_addc_co_u32_e64 v19, s[6:7], 0, v7, s[6:7]
	s_mov_b32 s6, 0x160000
	global_load_dword v26, v[18:19], off
	v_add_co_u32_e64 v18, s[6:7], s6, v6
	s_nop 1
	v_addc_co_u32_e64 v19, s[6:7], 0, v7, s[6:7]
	s_mov_b32 s6, 0x170000
	global_load_dword v25, v[18:19], off
	v_add_co_u32_e64 v18, s[6:7], s6, v6
	s_nop 1
	v_addc_co_u32_e64 v19, s[6:7], 0, v7, s[6:7]
	s_mov_b32 s6, 0x180000
	global_load_dword v24, v[18:19], off
	v_add_co_u32_e64 v18, s[6:7], s6, v6
	s_nop 1
	v_addc_co_u32_e64 v19, s[6:7], 0, v7, s[6:7]
	s_mov_b32 s6, 0x190000
	global_load_dword v23, v[18:19], off
	v_add_co_u32_e64 v18, s[6:7], s6, v6
	s_nop 1
	v_addc_co_u32_e64 v19, s[6:7], 0, v7, s[6:7]
	s_mov_b32 s6, 0x1a0000
	global_load_dword v22, v[18:19], off
	v_add_co_u32_e64 v18, s[6:7], s6, v6
	s_nop 1
	v_addc_co_u32_e64 v19, s[6:7], 0, v7, s[6:7]
	s_mov_b32 s6, 0x1b0000
	global_load_dword v21, v[18:19], off
	v_add_co_u32_e64 v18, s[6:7], s6, v6
	s_nop 1
	v_addc_co_u32_e64 v19, s[6:7], 0, v7, s[6:7]
	s_mov_b32 s6, 0x1c0000
	global_load_dword v20, v[18:19], off
	v_add_co_u32_e64 v18, s[6:7], s6, v6
	s_nop 1
	v_addc_co_u32_e64 v19, s[6:7], 0, v7, s[6:7]
	s_mov_b32 s6, 0x1d0000
	global_load_dword v48, v[18:19], off
	v_add_co_u32_e64 v18, s[6:7], s6, v6
	s_nop 1
	v_addc_co_u32_e64 v19, s[6:7], 0, v7, s[6:7]
	s_mov_b32 s6, 0x1e0000
	global_load_dword v49, v[18:19], off
	v_add_co_u32_e64 v18, s[6:7], s6, v6
	s_nop 1
	v_addc_co_u32_e64 v19, s[6:7], 0, v7, s[6:7]
	s_mov_b32 s6, 0x1f0000
	s_nop 0
	v_add_co_u32_e64 v6, s[6:7], s6, v6
	global_load_dword v18, v[18:19], off
	s_nop 0
	v_addc_co_u32_e64 v7, s[6:7], 0, v7, s[6:7]
	global_load_dword v7, v[6:7], off
	s_waitcnt vmcnt(0)
; #define LAS __attribute__((address_space(3)))
; __device__ __forceinline__ void transpose_item(const float* W, int K, int N, int NP, bf16* WT, LAS float* scr, int item, int lane, const LAS float* tab, long long* bias, int ldb, const float* kscale = nullptr) {
;     ...
;     for (int i = 0; i < 32; ++i) { if (!okn) wv_[i] = 0.f; if (kscale != nullptr) wv_[i] *= kscale[k0 + 2 * i + (lane >> 5)]; scr[(2 * i + (lane >> 5)) * 33 + (lane & 31)] = wv_[i]; }
;     if (tab != nullptr) {
;         const LAS float* tp = tab + k0 + (lane >> 5);
; #pragma unroll
;         for (int bp = 0; bp < 5; ++bp) { float s = 0.f;
; #pragma unroll
;             for (int i = 0; i < 32; ++i) s += tp[bp * 2048 + 2 * i] * wv_[i];
;             s += __shfl_xor(s, 32);
;             if (lane < 32) atomicAdd((unsigned long long*)(bias + (size_t)bp * ldb + n), (unsigned long long)(long long)(s * 4294967296.f)); }
	v_cndmask_b32_e32 v50, 0, v5, vcc
	v_cndmask_b32_e32 v51, 0, v47, vcc
	v_cndmask_b32_e32 v52, 0, v46, vcc
	ds_write2_b32 v17, v50, v51 offset1:66
	v_cndmask_b32_e32 v46, v52, v46, vcc
	v_cndmask_b32_e32 v47, v51, v47, vcc
	v_cndmask_b32_e32 v53, 0, v45, vcc
	v_cndmask_b32_e32 v54, 0, v44, vcc
	v_cndmask_b32_e32 v55, 0, v43, vcc
	v_cndmask_b32_e32 v56, 0, v42, vcc
	v_cndmask_b32_e32 v57, 0, v41, vcc
	v_cndmask_b32_e32 v58, 0, v40, vcc
	ds_write2_b32 v17, v52, v53 offset0:132 offset1:198
	v_cndmask_b32_e32 v41, v57, v41, vcc
	v_cndmask_b32_e32 v42, v56, v42, vcc
	v_cndmask_b32_e32 v43, v55, v43, vcc
	v_cndmask_b32_e32 v44, v54, v44, vcc
	v_cndmask_b32_e32 v45, v53, v45, vcc
	v_cndmask_b32_e32 v59, 0, v39, vcc
	v_cndmask_b32_e32 v60, 0, v38, vcc
	v_cndmask_b32_e32 v61, 0, v37, vcc
	v_cndmask_b32_e32 v62, 0, v36, vcc
	v_cndmask_b32_e32 v63, 0, v35, vcc
	v_cndmask_b32_e32 v64, 0, v34, vcc
	v_cndmask_b32_e32 v65, 0, v32, vcc
	v_cndmask_b32_e32 v66, 0, v31, vcc
	v_cndmask_b32_e32 v67, 0, v30, vcc
	v_cndmask_b32_e32 v68, 0, v29, vcc
	v_add_u32_e32 v6, 0x400, v17
	ds_write2_b32 v6, v54, v55 offset0:8 offset1:74
	ds_write2_b32 v6, v56, v57 offset0:140 offset1:206
	v_add_u32_e32 v6, 0x800, v17
	ds_write2_b32 v6, v58, v59 offset0:16 offset1:82
	ds_write2_b32 v6, v60, v61 offset0:148 offset1:214
	v_add_u32_e32 v6, 0xc00, v17
	ds_write2_b32 v6, v62, v63 offset0:24 offset1:90
	ds_write2_b32 v6, v64, v65 offset0:156 offset1:222
	v_add_u32_e32 v6, 0x1000, v17
	s_waitcnt vmcnt(12)
	v_cndmask_b32_e32 v69, 0, v28, vcc
	ds_write2_b32 v6, v66, v67 offset0:32 offset1:98
	ds_write2_b32 v6, v68, v69 offset0:164 offset1:230
	s_waitcnt vmcnt(11)
	v_cndmask_b32_e32 v70, 0, v27, vcc
	s_waitcnt vmcnt(10)
	v_cndmask_b32_e32 v71, 0, v26, vcc
	v_add_u32_e32 v6, 0x1400, v17
	ds_write2_b32 v6, v70, v71 offset0:40 offset1:106
	s_and_b32 s6, s13, 0xffffff00
	s_waitcnt vmcnt(9)
	v_cndmask_b32_e32 v72, 0, v25, vcc
	v_cndmask_b32_e32 v40, v58, v40, vcc
	v_cndmask_b32_e32 v39, v59, v39, vcc
	v_cndmask_b32_e32 v38, v60, v38, vcc
	v_cndmask_b32_e32 v37, v61, v37, vcc
	v_cndmask_b32_e32 v36, v62, v36, vcc
	v_cndmask_b32_e32 v35, v63, v35, vcc
	s_waitcnt vmcnt(8)
	v_cndmask_b32_e32 v73, 0, v24, vcc
	ds_write2_b32 v6, v72, v73 offset0:172 offset1:238
	v_add_u32_e32 v6, 0x1800, v17
	v_cndmask_b32_e32 v34, v64, v34, vcc
	v_cndmask_b32_e32 v32, v65, v32, vcc
	v_cndmask_b32_e32 v31, v66, v31, vcc
	v_cndmask_b32_e32 v30, v67, v30, vcc
	s_waitcnt vmcnt(7)
	v_cndmask_b32_e32 v74, 0, v23, vcc
	v_cndmask_b32_e32 v29, v68, v29, vcc
	v_cndmask_b32_e32 v28, v69, v28, vcc
	v_cndmask_b32_e32 v27, v70, v27, vcc
	v_cndmask_b32_e32 v26, v71, v26, vcc
	v_cndmask_b32_e32 v25, v72, v25, vcc
	v_cndmask_b32_e32 v24, v73, v24, vcc
	s_waitcnt vmcnt(6)
	v_cndmask_b32_e32 v75, 0, v22, vcc
	ds_write2_b32 v6, v74, v75 offset0:48 offset1:114
	v_cndmask_b32_e32 v23, v74, v23, vcc
	v_cndmask_b32_e32 v22, v75, v22, vcc
	s_waitcnt vmcnt(5)
	v_cndmask_b32_e32 v76, 0, v21, vcc
	v_cndmask_b32_e32 v21, v76, v21, vcc
	s_waitcnt vmcnt(4)
	v_cndmask_b32_e32 v77, 0, v20, vcc
	ds_write2_b32 v6, v76, v77 offset0:180 offset1:246
	v_cndmask_b32_e32 v20, v77, v20, vcc
	s_waitcnt vmcnt(3)
	v_cndmask_b32_e32 v19, 0, v48, vcc
	s_waitcnt vmcnt(2)
	v_cndmask_b32_e32 v78, 0, v49, vcc
	ds_write2_b32 v79, v19, v78 offset0:56 offset1:122
	v_cndmask_b32_e32 v19, v19, v48, vcc
	v_cndmask_b32_e32 v48, v50, v5, vcc
	v_ashrrev_i32_e32 v5, 31, v4
	v_lshl_add_u64 v[4:5], v[4:5], 3, s[10:11]
	s_waitcnt vmcnt(1)
	v_cndmask_b32_e32 v80, 0, v18, vcc
	v_cndmask_b32_e32 v6, v80, v18, vcc
	v_cndmask_b32_e32 v18, v78, v49, vcc
	s_waitcnt vmcnt(0)
	v_cndmask_b32_e32 v7, 0, v7, vcc
	ds_write2_b32 v79, v80, v7 offset0:188 offset1:254
	v_add_u32_e32 v49, s6, v12
	ds_read2_b32 v[50:51], v49 offset1:2
	ds_read2_b32 v[52:53], v49 offset0:4 offset1:6
	ds_read2_b32 v[54:55], v49 offset0:8 offset1:10
	ds_read2_b32 v[56:57], v49 offset0:12 offset1:14
	s_waitcnt lgkmcnt(3)
	v_fma_f32 v50, v50, v48, 0
	v_fmac_f32_e32 v50, v51, v47
	s_waitcnt lgkmcnt(2)
	v_fmac_f32_e32 v50, v52, v46
	v_fmac_f32_e32 v50, v53, v45
	ds_read2_b32 v[52:53], v49 offset0:16 offset1:18
	s_waitcnt lgkmcnt(2)
	v_fmac_f32_e32 v50, v54, v44
	v_fmac_f32_e32 v50, v55, v43
	s_waitcnt lgkmcnt(1)
	v_fmac_f32_e32 v50, v56, v42
	v_fmac_f32_e32 v50, v57, v41
	s_waitcnt lgkmcnt(0)
	v_fmac_f32_e32 v50, v52, v40
	v_fmac_f32_e32 v50, v53, v39
	ds_read2_b32 v[52:53], v49 offset0:20 offset1:22
	s_waitcnt lgkmcnt(0)
	v_fmac_f32_e32 v50, v52, v38
	v_fmac_f32_e32 v50, v53, v37
	ds_read2_b32 v[52:53], v49 offset0:24 offset1:26
	s_waitcnt lgkmcnt(0)
	v_fmac_f32_e32 v50, v52, v36
	v_fmac_f32_e32 v50, v53, v35
	ds_read2_b32 v[52:53], v49 offset0:28 offset1:30
	s_waitcnt lgkmcnt(0)
	v_fmac_f32_e32 v50, v52, v34
	v_fmac_f32_e32 v50, v53, v32
	ds_read2_b32 v[52:53], v49 offset0:32 offset1:34
	s_waitcnt lgkmcnt(0)
	v_fmac_f32_e32 v50, v52, v31
	v_fmac_f32_e32 v50, v53, v30
	ds_read2_b32 v[52:53], v49 offset0:36 offset1:38
	s_waitcnt lgkmcnt(0)
	v_fmac_f32_e32 v50, v52, v29
	v_fmac_f32_e32 v50, v53, v28
	ds_read2_b32 v[52:53], v49 offset0:40 offset1:42
	s_waitcnt lgkmcnt(0)
	v_fmac_f32_e32 v50, v52, v27
	v_fmac_f32_e32 v50, v53, v26
	ds_read2_b32 v[52:53], v49 offset0:44 offset1:46
	s_waitcnt lgkmcnt(0)
	v_fmac_f32_e32 v50, v52, v25
	v_fmac_f32_e32 v50, v53, v24
	ds_read2_b32 v[52:53], v49 offset0:48 offset1:50
	s_waitcnt lgkmcnt(0)
	v_fmac_f32_e32 v50, v52, v23
	v_fmac_f32_e32 v50, v53, v22
	ds_read2_b32 v[52:53], v49 offset0:52 offset1:54
	s_waitcnt lgkmcnt(0)
	v_fmac_f32_e32 v50, v52, v21
	v_fmac_f32_e32 v50, v53, v20
	ds_read2_b32 v[52:53], v49 offset0:56 offset1:58
	s_waitcnt lgkmcnt(0)
	v_fmac_f32_e32 v50, v52, v19
	v_fmac_f32_e32 v50, v53, v18
	ds_read2_b32 v[52:53], v49 offset0:60 offset1:62
	s_waitcnt lgkmcnt(0)
	v_fmac_f32_e32 v50, v52, v6
	v_fmac_f32_e32 v50, v53, v7
	ds_bpermute_b32 v51, v13, v50
	s_and_saveexec_b64 s[6:7], s[4:5]
	s_cbranch_execz .LBB0_1357
	s_waitcnt lgkmcnt(0)
	v_add_f32_e32 v50, v50, v51
	v_mul_f32_e32 v50, 0x4f800000, v50
	v_trunc_f32_e32 v50, v50
	v_mul_f32_e64 v51, |v50|, s97
	v_floor_f32_e32 v51, v51
	v_fma_f32 v52, v51, s74, |v50|
	v_cvt_u32_f32_e32 v52, v52
	v_cvt_u32_f32_e32 v51, v51
	v_ashrrev_i32_e32 v53, 31, v50
	v_xor_b32_e32 v50, v52, v53
	v_xor_b32_e32 v51, v51, v53
	v_sub_co_u32_e32 v50, vcc, v50, v53
	s_nop 1
	v_subb_co_u32_e32 v51, vcc, v51, v53, vcc
	global_atomic_add_x2 v[4:5], v[50:51], off
